# v32 = v29 without the unit-final barrier on prefetched causal-unit transitions (the next unit's first barrier closes the previous unit)
# speedup vs baseline: 1.0007x; 1.0007x over previous
.Lnbp_skip:
	s_waitcnt lgkmcnt(0)
	ds_read_b128 v[32:35], v215 offset:128
	ds_read_b128 v[36:39], v215 offset:160
	s_waitcnt lgkmcnt(1)
	v_rcp_f32_e32 v40, v32
	v_rcp_f32_e32 v41, v33
	v_mul_f32_e32 v0, v0, v40
	v_cvt_pk_bf16_f32 v0, v0, s0
	v_rcp_f32_e32 v42, v34
	ds_write_b16 v217, v0 offset:64
	v_mul_f32_e32 v0, v17, v41
	v_cvt_pk_bf16_f32 v0, v0, s0
	ds_write_b16 v217, v0 offset:128
	v_mul_f32_e32 v0, v1, v41
	v_cvt_pk_bf16_f32 v0, v0, s0
	v_rcp_f32_e32 v43, v35
	ds_write_b16 v217, v0 offset:192
	v_mul_f32_e32 v0, v18, v42
	v_cvt_pk_bf16_f32 v0, v0, s0
	ds_write_b16 v217, v0 offset:256
	v_mul_f32_e32 v0, v2, v42
	v_cvt_pk_bf16_f32 v0, v0, s0
	s_waitcnt lgkmcnt(4)
	v_rcp_f32_e32 v44, v36
	ds_write_b16 v217, v0 offset:320
	v_mul_f32_e32 v0, v19, v43
	v_cvt_pk_bf16_f32 v0, v0, s0
	ds_write_b16 v217, v0 offset:384
	v_mul_f32_e32 v0, v3, v43
	v_cvt_pk_bf16_f32 v0, v0, s0
	v_rcp_f32_e32 v45, v37
	ds_write_b16 v217, v0 offset:448
	v_mul_f32_e32 v0, v20, v44
	v_cvt_pk_bf16_f32 v0, v0, s0
	ds_write_b16 v217, v0 offset:1024
	v_mul_f32_e32 v0, v4, v44
	v_cvt_pk_bf16_f32 v0, v0, s0
	v_rcp_f32_e32 v46, v38
	ds_write_b16 v217, v0 offset:1088
	v_mul_f32_e32 v0, v21, v45
	v_cvt_pk_bf16_f32 v0, v0, s0
	ds_write_b16 v217, v0 offset:1152
	v_mul_f32_e32 v0, v5, v45
	ds_read_b128 v[32:35], v215 offset:192
	v_cvt_pk_bf16_f32 v0, v0, s0
	v_rcp_f32_e32 v47, v39
	ds_write_b16 v217, v0 offset:1216
	v_mul_f32_e32 v0, v22, v46
	v_cvt_pk_bf16_f32 v0, v0, s0
	ds_write_b16 v217, v0 offset:1280
	v_mul_f32_e32 v0, v6, v46
	v_cvt_pk_bf16_f32 v0, v0, s0
	ds_read_b128 v[36:39], v215 offset:224
	s_waitcnt lgkmcnt(3)
	v_rcp_f32_e32 v32, v32
	ds_write_b16 v217, v0 offset:1344
	v_mul_f32_e32 v0, v23, v47
	v_cvt_pk_bf16_f32 v0, v0, s0
	ds_write_b16 v217, v0 offset:1408
	v_mul_f32_e32 v0, v7, v47
	v_cvt_pk_bf16_f32 v0, v0, s0
	v_rcp_f32_e32 v33, v33
	ds_write_b16 v217, v0 offset:1472
	v_mul_f32_e32 v0, v24, v32
	v_cvt_pk_bf16_f32 v0, v0, s0
	ds_write_b16 v217, v0 offset:2048
	v_mul_f32_e32 v0, v8, v32
	v_cvt_pk_bf16_f32 v0, v0, s0
	v_rcp_f32_e32 v34, v34
	ds_write_b16 v217, v0 offset:2112
	v_mul_f32_e32 v0, v25, v33
	v_cvt_pk_bf16_f32 v0, v0, s0
	ds_write_b16 v217, v0 offset:2176
	v_mul_f32_e32 v0, v9, v33
	v_cvt_pk_bf16_f32 v0, v0, s0
	v_rcp_f32_e32 v35, v35
	ds_write_b16 v217, v0 offset:2240
	v_mul_f32_e32 v0, v26, v34
	v_cvt_pk_bf16_f32 v0, v0, s0
	ds_write_b16 v217, v0 offset:2304
	v_mul_f32_e32 v0, v10, v34
	v_cvt_pk_bf16_f32 v0, v0, s0
	s_waitcnt lgkmcnt(8)
	v_rcp_f32_e32 v36, v36
	ds_write_b16 v217, v0 offset:2368
	v_mul_f32_e32 v0, v27, v35
	v_cvt_pk_bf16_f32 v0, v0, s0
	ds_write_b16 v217, v0 offset:2432
	v_mul_f32_e32 v0, v11, v35
	v_cvt_pk_bf16_f32 v0, v0, s0
	v_rcp_f32_e32 v37, v37
	ds_write_b16 v217, v0 offset:2496
	v_mul_f32_e32 v0, v28, v36
	v_cvt_pk_bf16_f32 v0, v0, s0
	ds_write_b16 v217, v0 offset:3072
	v_mul_f32_e32 v0, v12, v36
	v_cvt_pk_bf16_f32 v0, v0, s0
	v_rcp_f32_e32 v38, v38
	ds_write_b16 v217, v0 offset:3136
	v_mul_f32_e32 v0, v29, v37
	v_cvt_pk_bf16_f32 v0, v0, s0
	ds_write_b16 v217, v0 offset:3200
	v_mul_f32_e32 v0, v13, v37
	v_cvt_pk_bf16_f32 v0, v0, s0
	v_rcp_f32_e32 v39, v39
	ds_write_b16 v217, v0 offset:3264
	v_mul_f32_e32 v0, v30, v38
	v_cvt_pk_bf16_f32 v0, v0, s0
	ds_write_b16 v217, v0 offset:3328
	v_mul_f32_e32 v0, v14, v38
	v_cvt_pk_bf16_f32 v0, v0, s0
	ds_write_b16 v217, v0 offset:3392
	v_mul_f32_e32 v0, v31, v39
	v_cvt_pk_bf16_f32 v0, v0, s0
	v_mul_f32_e32 v16, v16, v40
	ds_write_b16 v217, v0 offset:3456
	v_mul_f32_e32 v0, v15, v39
	v_cvt_pk_bf16_f32 v16, v16, s0
	v_cvt_pk_bf16_f32 v0, v0, s0
	ds_write_b16 v217, v16
	ds_write_b16 v217, v0 offset:3520
	v_mov_b32_e32 v16, v80
	v_mov_b32_e32 v17, v81
	v_lshlrev_b64 v[140:141], 1, v[154:155]
	s_waitcnt lgkmcnt(0)
	v_lshl_add_u64 v[0:1], v[16:17], 0, v[140:141]
	global_load_dwordx4 v[0:3], v[0:1], off
	v_lshlrev_b64 v[142:143], 1, v[156:157]
	v_lshl_add_u64 v[4:5], v[16:17], 0, v[142:143]
	global_load_dwordx4 v[4:7], v[4:5], off
	v_lshlrev_b64 v[166:167], 1, v[158:159]
	v_lshl_add_u64 v[8:9], v[16:17], 0, v[166:167]
	global_load_dwordx4 v[8:11], v[8:9], off
	v_lshlrev_b64 v[168:169], 1, v[160:161]
	v_lshl_add_u64 v[16:17], v[16:17], 0, v[168:169]
	global_load_dwordx4 v[16:19], v[16:17], off
	ds_read_b128 v[12:15], v177
	v_mov_b32_e32 v20, v82
	v_mov_b32_e32 v21, v83
	s_waitcnt lgkmcnt(0)
	v_lshlrev_b32_e32 v22, 16, v12
	v_and_b32_e32 v23, 0xffff0000, v12
	v_lshlrev_b32_e32 v12, 16, v13
	v_and_b32_e32 v13, 0xffff0000, v13
	s_waitcnt vmcnt(3)
	v_lshlrev_b32_e32 v24, 16, v0
	v_and_b32_e32 v25, 0xffff0000, v0
	v_pk_mul_f32 v[22:23], v[22:23], v[24:25]
	v_lshlrev_b32_e32 v24, 16, v3
	v_cvt_pk_bf16_f32 v0, v22, v23
	v_lshlrev_b32_e32 v22, 16, v1
	v_and_b32_e32 v23, 0xffff0000, v1
	v_pk_mul_f32 v[12:13], v[12:13], v[22:23]
	v_lshlrev_b32_e32 v22, 16, v2
	v_cvt_pk_bf16_f32 v1, v12, v13
	v_lshlrev_b32_e32 v12, 16, v14
	v_and_b32_e32 v13, 0xffff0000, v14
	v_and_b32_e32 v23, 0xffff0000, v2
	v_pk_mul_f32 v[12:13], v[12:13], v[22:23]
	v_lshlrev_b32_e32 v22, 16, v15
	v_cvt_pk_bf16_f32 v2, v12, v13
	v_and_b32_e32 v23, 0xffff0000, v15
	ds_read_b128 v[12:15], v176
	v_and_b32_e32 v25, 0xffff0000, v3
	v_pk_mul_f32 v[22:23], v[22:23], v[24:25]
	s_nop 0
	v_cvt_pk_bf16_f32 v3, v22, v23
	v_lshl_add_u64 v[22:23], v[20:21], 0, v[140:141]
	global_store_dwordx4 v[22:23], v[0:3], off sc1
	s_waitcnt lgkmcnt(0)
	s_nop 0
	v_lshlrev_b32_e32 v0, 16, v12
	v_and_b32_e32 v1, 0xffff0000, v12
	s_waitcnt vmcnt(3)
	v_lshlrev_b32_e32 v2, 16, v4
	v_and_b32_e32 v3, 0xffff0000, v4
	v_pk_mul_f32 v[0:1], v[0:1], v[2:3]
	v_lshlrev_b32_e32 v2, 16, v13
	v_and_b32_e32 v3, 0xffff0000, v13
	v_lshlrev_b32_e32 v4, 16, v5
	v_and_b32_e32 v5, 0xffff0000, v5
	v_pk_mul_f32 v[2:3], v[2:3], v[4:5]
	v_cvt_pk_bf16_f32 v0, v0, v1
	v_cvt_pk_bf16_f32 v1, v2, v3
	v_lshlrev_b32_e32 v2, 16, v14
	v_and_b32_e32 v3, 0xffff0000, v14
	v_lshlrev_b32_e32 v4, 16, v6
	v_and_b32_e32 v5, 0xffff0000, v6
	v_pk_mul_f32 v[2:3], v[2:3], v[4:5]
	v_lshlrev_b32_e32 v12, 16, v15
	v_and_b32_e32 v13, 0xffff0000, v15
	v_lshlrev_b32_e32 v14, 16, v7
	v_and_b32_e32 v15, 0xffff0000, v7
	ds_read_b128 v[4:7], v175
	v_pk_mul_f32 v[12:13], v[12:13], v[14:15]
	v_cvt_pk_bf16_f32 v2, v2, v3
	v_cvt_pk_bf16_f32 v3, v12, v13
	v_lshl_add_u64 v[12:13], v[20:21], 0, v[142:143]
	global_store_dwordx4 v[12:13], v[0:3], off sc1
	s_waitcnt lgkmcnt(0)
	s_nop 0
	v_lshlrev_b32_e32 v0, 16, v4
	v_and_b32_e32 v1, 0xffff0000, v4
	s_waitcnt vmcnt(3)
	v_lshlrev_b32_e32 v2, 16, v8
	v_and_b32_e32 v3, 0xffff0000, v8
	v_pk_mul_f32 v[0:1], v[0:1], v[2:3]
	v_lshlrev_b32_e32 v2, 16, v5
	v_and_b32_e32 v3, 0xffff0000, v5
	v_lshlrev_b32_e32 v4, 16, v9
	v_and_b32_e32 v5, 0xffff0000, v9
	v_pk_mul_f32 v[2:3], v[2:3], v[4:5]
	v_cvt_pk_bf16_f32 v0, v0, v1
	v_cvt_pk_bf16_f32 v1, v2, v3
	v_lshlrev_b32_e32 v2, 16, v6
	v_and_b32_e32 v3, 0xffff0000, v6
	v_lshlrev_b32_e32 v4, 16, v10
	v_and_b32_e32 v5, 0xffff0000, v10
	v_pk_mul_f32 v[2:3], v[2:3], v[4:5]
	v_lshlrev_b32_e32 v8, 16, v7
	v_and_b32_e32 v9, 0xffff0000, v7
	ds_read_b128 v[4:7], v174
	v_lshlrev_b32_e32 v10, 16, v11
	v_and_b32_e32 v11, 0xffff0000, v11
	v_pk_mul_f32 v[8:9], v[8:9], v[10:11]
	v_cvt_pk_bf16_f32 v2, v2, v3
	v_cvt_pk_bf16_f32 v3, v8, v9
	v_lshl_add_u64 v[8:9], v[20:21], 0, v[166:167]
	global_store_dwordx4 v[8:9], v[0:3], off sc1
	s_waitcnt lgkmcnt(0)
	s_nop 0
	v_lshlrev_b32_e32 v0, 16, v4
	v_and_b32_e32 v1, 0xffff0000, v4
	s_waitcnt vmcnt(3)
	v_lshlrev_b32_e32 v2, 16, v16
	v_and_b32_e32 v3, 0xffff0000, v16
	v_pk_mul_f32 v[0:1], v[0:1], v[2:3]
	v_lshlrev_b32_e32 v2, 16, v5
	v_and_b32_e32 v3, 0xffff0000, v5
	v_lshlrev_b32_e32 v4, 16, v17
	v_and_b32_e32 v5, 0xffff0000, v17
	v_pk_mul_f32 v[2:3], v[2:3], v[4:5]
	v_cvt_pk_bf16_f32 v0, v0, v1
	v_cvt_pk_bf16_f32 v1, v2, v3
	v_lshlrev_b32_e32 v2, 16, v6
	v_and_b32_e32 v3, 0xffff0000, v6
	v_lshlrev_b32_e32 v4, 16, v18
	v_and_b32_e32 v5, 0xffff0000, v18
	v_pk_mul_f32 v[2:3], v[2:3], v[4:5]
	v_lshlrev_b32_e32 v4, 16, v7
	v_and_b32_e32 v5, 0xffff0000, v7
	v_lshlrev_b32_e32 v6, 16, v19
	v_and_b32_e32 v7, 0xffff0000, v19
	v_pk_mul_f32 v[4:5], v[4:5], v[6:7]
	v_cvt_pk_bf16_f32 v2, v2, v3
	v_cvt_pk_bf16_f32 v3, v4, v5
	v_lshl_add_u64 v[4:5], v[20:21], 0, v[168:169]
	global_store_dwordx4 v[4:5], v[0:3], off sc1
	s_cmp_eq_u32 s78, 3
	s_cbranch_scc0 .Lnbp_nobar
	s_waitcnt lgkmcnt(0)
	s_barrier
	s_branch .LBB0_668
.Lnbp_nobar:
	s_waitcnt lgkmcnt(0)
	v_mov_b32_e32 v0, v48
	v_mov_b32_e32 v1, v49
	v_mov_b32_e32 v2, v50
	v_mov_b32_e32 v3, v51
	v_mov_b32_e32 v4, v52
	v_mov_b32_e32 v5, v53
	v_mov_b32_e32 v6, v54
	v_mov_b32_e32 v7, v55
	v_mov_b32_e32 v8, v56
	v_mov_b32_e32 v9, v57
	v_mov_b32_e32 v10, v58
	v_mov_b32_e32 v11, v59
	v_mov_b32_e32 v12, v60
	v_mov_b32_e32 v13, v61
	v_mov_b32_e32 v14, v62
	v_mov_b32_e32 v15, v63
	v_mov_b32_e32 v16, v64
	v_mov_b32_e32 v17, v65
	v_mov_b32_e32 v18, v66
	v_mov_b32_e32 v19, v67
	v_mov_b32_e32 v20, v68
	v_mov_b32_e32 v21, v69
	v_mov_b32_e32 v22, v70
	v_mov_b32_e32 v23, v71
	s_branch .Lnbp_join
